# P10 K-loop MFMA/LDS interleave: next K-tile's first fragment LDS reads issued right after the barrier before the trailing MFMAs, remaining first-group reads before the address math and global loads
# speedup vs baseline: 1.0108x; 1.0108x over previous
.LBB0_1888:
	s_ashr_i32 s0, s49, 31
	s_lshr_b32 s0, s0, 30
	s_add_i32 s0, s49, s0
	s_ashr_i32 s15, s0, 2
	s_and_b32 s1, s0, -4
	s_ashr_i32 s0, s0, 6
	s_sub_i32 s16, s49, s1
	s_ashr_i32 s1, s0, 31
	s_lshl_b32 s14, s15, 8
	s_lshl_b64 s[0:1], s[0:1], 23
	s_add_u32 s17, s3, s0
	s_addc_u32 s18, s26, s1
	s_lshl_b32 s15, s15, 9
	s_and_b32 s24, s15, 0x1e00
	s_add_u32 s20, s17, s24
	s_addc_u32 s21, s18, 0
	s_ashr_i32 s17, s16, 31
	s_lshl_b64 s[18:19], s[16:17], 19
	s_add_u32 s22, s27, s18
	s_getreg_b32 s15, hwreg(HW_REG_HW_ID, 0, 6)
	s_addc_u32 s23, s48, s19
	s_lshl_b32 s15, s15, 2
	s_and_b32 s15, s15, 0xfc
	s_add_i32 s15, s15, 0
	s_add_i32 s15, s15, 0x256c0
	v_mov_b32_e32 v0, s15
	ds_read_b32 v0, v0
	v_mov_b32_e32 v41, v173
	v_mov_b32_e32 v96, 0
	v_mov_b32_e32 v97, v173
	v_mov_b32_e32 v98, v173
	s_waitcnt lgkmcnt(0)
	v_readfirstlane_b32 s15, v0
	v_mbcnt_lo_u32_b32 v0, -1, 0
	v_mbcnt_hi_u32_b32 v0, -1, v0
	v_mov_b32_e32 v99, v173
	s_waitcnt vmcnt(0)
	v_mov_b32_e32 v100, v173
	v_lshl_add_u32 v174, s15, 6, v0
	v_mov_b32_e32 v101, v173
	v_ashrrev_i32_e32 v32, 5, v174
	v_ashrrev_i32_e32 v33, 31, v32
	v_ashrrev_i32_e32 v36, 3, v174
	v_and_b32_e32 v175, 31, v174
	v_lshlrev_b64 v[34:35], 13, v[32:33]
	v_ashrrev_i32_e32 v37, 31, v36
	v_lshl_add_u64 v[0:1], s[20:21], 0, v[34:35]
	v_lshlrev_b32_e32 v172, 4, v175
	v_and_b32_e32 v185, 7, v174
	v_lshlrev_b64 v[38:39], 11, v[36:37]
	v_lshl_add_u64 v[160:161], v[0:1], 0, v[172:173]
	v_lshl_add_u64 v[0:1], s[22:23], 0, v[38:39]
	v_lshlrev_b32_e32 v40, 4, v185
	v_lshl_add_u64 v[162:163], v[0:1], 0, v[40:41]
	v_add_co_u32_e32 v0, vcc, s60, v160
	v_readfirstlane_b32 s15, v174
	s_nop 0
	v_addc_co_u32_e32 v1, vcc, 0, v161, vcc
	v_add_co_u32_e32 v4, vcc, s61, v160
	v_lshlrev_b32_e32 v41, 2, v174
	s_nop 0
	v_addc_co_u32_e32 v5, vcc, 0, v161, vcc
	v_add_co_u32_e32 v16, vcc, s62, v160
	global_load_dwordx4 v[0:3], v[0:1], off
	s_nop 0
	global_load_dwordx4 v[4:7], v[4:5], off
	v_addc_co_u32_e32 v17, vcc, 0, v161, vcc
	v_add_co_u32_e32 v164, vcc, s60, v162
	global_load_dwordx4 v[8:11], v[160:161], off
	global_load_dwordx4 v[12:15], v[162:163], off
	v_addc_co_u32_e32 v165, vcc, 0, v163, vcc
	v_add_co_u32_e32 v166, vcc, s61, v162
	global_load_dwordx4 v[16:19], v[16:17], off
	s_nop 0
	global_load_dwordx4 v[20:23], v[164:165], off
	v_addc_co_u32_e32 v167, vcc, 0, v163, vcc
	v_add_co_u32_e32 v168, vcc, s62, v162
	s_ashr_i32 s21, s15, 6
	s_nop 0
	v_addc_co_u32_e32 v169, vcc, 0, v163, vcc
	global_load_dwordx4 v[24:27], v[166:167], off
	global_load_dwordx4 v[28:31], v[168:169], off
	s_ashr_i32 s15, s15, 1
	v_and_b32_e32 v41, 12, v41
	v_and_b32_e32 v33, 16, v174
	s_and_b32 s20, s15, 0xffffff80
	s_and_b32 s15, s21, 3
	v_mad_u64_u32 v[170:171], s[22:23], v32, s58, v[172:173]
	v_mad_u64_u32 v[176:177], s[22:23], v36, s59, v[40:41]
	v_bfe_u32 v186, v174, 5, 1
	v_bfe_u32 v37, v174, 2, 2
	v_or3_b32 v32, v41, v33, s20
	s_lshl_b32 s22, s15, 6
	v_lshl_or_b32 v37, v186, 3, v37
	v_lshlrev_b32_e32 v189, 4, v186
	v_add_u32_e32 v177, 0, v170
	v_lshlrev_b32_e32 v192, 1, v32
	v_or_b32_e32 v32, s22, v175
	v_lshl_add_u64 v[180:181], s[18:19], 0, v[38:39]
	v_lshl_add_u64 v[182:183], s[0:1], 0, v[34:35]
	v_and_b32_e32 v187, 63, v174
	v_lshlrev_b32_e32 v178, 3, v185
	v_mul_u32_u24_e32 v190, 0x240, v37
	v_add_u32_e32 v171, 0, v176
	v_mad_u32_u24 v188, v37, s58, v192
	v_mul_u32_u24_e32 v191, 0x90, v32
	v_mad_u32_u24 v193, v32, s59, v189
	v_or_b32_e32 v180, v180, v40
	v_or3_b32 v182, v182, s24, v172
	s_mov_b32 s0, 0
	v_mov_b32_e32 v102, v173
	v_mov_b32_e32 v103, v173
	v_mov_b32_e32 v104, v173
	v_mov_b32_e32 v105, v173
	v_mov_b32_e32 v106, v173
	v_mov_b32_e32 v107, v173
	v_mov_b32_e32 v108, v173
	v_mov_b32_e32 v109, v173
	s_waitcnt vmcnt(5)
	ds_write_b128 v177, v[8:11]
	ds_write_b128 v177, v[0:3] offset:9216
	ds_write_b128 v177, v[4:7] offset:18432
	s_waitcnt vmcnt(3)
	ds_write_b128 v177, v[16:19] offset:27648
	ds_write_b128 v171, v[12:15] offset:36864
	s_waitcnt vmcnt(2)
	ds_write_b128 v171, v[20:23] offset:46080
	s_waitcnt vmcnt(1)
	ds_write_b128 v171, v[24:27] offset:55296
	s_waitcnt vmcnt(0)
	ds_write_b128 v171, v[28:31] offset:64512
	v_mov_b32_e32 v110, v173
	v_mov_b32_e32 v111, v173
	v_mov_b32_e32 v112, 0
	v_mov_b32_e32 v113, v173
	v_mov_b32_e32 v114, v173
	v_mov_b32_e32 v115, v173
	v_mov_b32_e32 v116, v173
	v_mov_b32_e32 v117, v173
	v_mov_b32_e32 v118, v173
	v_mov_b32_e32 v119, v173
	v_mov_b32_e32 v120, v173
	v_mov_b32_e32 v121, v173
	v_mov_b32_e32 v122, v173
	v_mov_b32_e32 v123, v173
	v_mov_b32_e32 v124, v173
	v_mov_b32_e32 v125, v173
	v_mov_b32_e32 v126, v173
	v_mov_b32_e32 v127, v173
	v_mov_b32_e32 v64, 0
	v_mov_b32_e32 v65, v173
	v_mov_b32_e32 v66, v173
	v_mov_b32_e32 v67, v173
	v_mov_b32_e32 v68, v173
	v_mov_b32_e32 v69, v173
	v_mov_b32_e32 v70, v173
	v_mov_b32_e32 v71, v173
	v_mov_b32_e32 v72, v173
	v_mov_b32_e32 v73, v173
	v_mov_b32_e32 v74, v173
	v_mov_b32_e32 v75, v173
	v_mov_b32_e32 v76, v173
	v_mov_b32_e32 v77, v173
	v_mov_b32_e32 v78, v173
	v_mov_b32_e32 v79, v173
	v_mov_b32_e32 v80, 0
	v_mov_b32_e32 v81, v173
	v_mov_b32_e32 v82, v173
	v_mov_b32_e32 v83, v173
	v_mov_b32_e32 v84, v173
	v_mov_b32_e32 v85, v173
	v_mov_b32_e32 v86, v173
	v_mov_b32_e32 v87, v173
	v_mov_b32_e32 v88, v173
	v_mov_b32_e32 v89, v173
	v_mov_b32_e32 v90, v173
	v_mov_b32_e32 v91, v173
	v_mov_b32_e32 v92, v173
	v_mov_b32_e32 v93, v173
	v_mov_b32_e32 v94, v173
	v_mov_b32_e32 v95, v173
	v_mov_b32_e32 v32, 0
	v_mov_b32_e32 v33, v173
	v_mov_b32_e32 v34, v173
	v_mov_b32_e32 v35, v173
	v_mov_b32_e32 v36, v173
	v_mov_b32_e32 v37, v173
	v_mov_b32_e32 v38, v173
	v_mov_b32_e32 v39, v173
	v_mov_b32_e32 v40, v173
	v_mov_b32_e32 v41, v173
	v_mov_b32_e32 v42, v173
	v_mov_b32_e32 v43, v173
	v_mov_b32_e32 v44, v173
	v_mov_b32_e32 v45, v173
	v_mov_b32_e32 v46, v173
	v_mov_b32_e32 v47, v173
	v_mov_b32_e32 v48, 0
	v_mov_b32_e32 v49, v173
	v_mov_b32_e32 v50, v173
	v_mov_b32_e32 v51, v173
	v_mov_b32_e32 v52, v173
	v_mov_b32_e32 v53, v173
	v_mov_b32_e32 v54, v173
	v_mov_b32_e32 v55, v173
	v_mov_b32_e32 v56, v173
	v_mov_b32_e32 v57, v173
	v_mov_b32_e32 v58, v173
	v_mov_b32_e32 v59, v173
	v_mov_b32_e32 v60, v173
	v_mov_b32_e32 v61, v173
	v_mov_b32_e32 v62, v173
	v_mov_b32_e32 v63, v173
	v_mov_b32_e32 v0, 0
	v_mov_b32_e32 v1, v173
	v_mov_b32_e32 v2, v173
	v_mov_b32_e32 v3, v173
	v_mov_b32_e32 v4, v173
	v_mov_b32_e32 v5, v173
	v_mov_b32_e32 v6, v173
	v_mov_b32_e32 v7, v173
	v_mov_b32_e32 v8, v173
	v_mov_b32_e32 v9, v173
	v_mov_b32_e32 v10, v173
	v_mov_b32_e32 v11, v173
	v_mov_b32_e32 v12, v173
	v_mov_b32_e32 v13, v173
	v_mov_b32_e32 v14, v173
	v_mov_b32_e32 v15, v173
	v_mov_b32_e32 v16, 0
	v_mov_b32_e32 v17, v173
	v_mov_b32_e32 v18, v173
	v_mov_b32_e32 v19, v173
	v_mov_b32_e32 v20, v173
	v_mov_b32_e32 v21, v173
	v_mov_b32_e32 v22, v173
	v_mov_b32_e32 v23, v173
	v_mov_b32_e32 v24, v173
	v_mov_b32_e32 v25, v173
	v_mov_b32_e32 v26, v173
	v_mov_b32_e32 v27, v173
	v_mov_b32_e32 v28, v173
	v_mov_b32_e32 v29, v173
	v_mov_b32_e32 v30, v173
	v_mov_b32_e32 v31, v173
	s_waitcnt lgkmcnt(0)
	s_barrier
	ds_read_b64_tr_b16 v[196:197], v188 offset:2304
	ds_read_b64_tr_b16 v[194:195], v188
	ds_read_b128 v[210:213], v193 offset:36864
	ds_read_b128 v[218:221], v193 offset:41472
.LBB0_1889:
	s_add_i32 s1, s0, 1
	s_bitcmp1_b32 s0, 0
	s_cselect_b32 s0, 0x12000, 0
	s_add_i32 s0, s0, 0
	v_add_u32_e32 v172, s0, v188
	v_add_u32_e32 v226, s0, v193
	ds_read_b64_tr_b16 v[198:199], v172 offset:64
	ds_read_b64_tr_b16 v[202:203], v172 offset:128
	ds_read_b64_tr_b16 v[206:207], v172 offset:192
	ds_read_b64_tr_b16 v[200:201], v172 offset:2368
	ds_read_b64_tr_b16 v[204:205], v172 offset:2432
	ds_read_b64_tr_b16 v[208:209], v172 offset:2496
	ds_read_b128 v[214:217], v226 offset:36896
	ds_read_b128 v[222:225], v226 offset:41504
	v_lshl_add_u64 v[136:137], s[78:79], 0, v[182:183]
	v_add_co_u32_e32 v128, vcc, s63, v136
	v_lshl_add_u64 v[152:153], s[78:79], 0, v[180:181]
	s_nop 0
	v_addc_co_u32_e32 v129, vcc, 0, v137, vcc
	v_add_co_u32_e32 v132, vcc, s64, v136
	s_nop 0
	s_nop 0
	v_addc_co_u32_e32 v133, vcc, 0, v137, vcc
	v_add_co_u32_e32 v138, vcc, s65, v136
	global_load_dwordx4 v[128:131], v[128:129], off
	s_nop 0
	global_load_dwordx4 v[132:135], v[132:133], off
	v_addc_co_u32_e32 v139, vcc, 0, v137, vcc
	v_add_co_u32_e32 v140, vcc, s66, v136
	s_nop 1
	v_addc_co_u32_e32 v141, vcc, 0, v137, vcc
	v_add_co_u32_e32 v144, vcc, s67, v152
	global_load_dwordx4 v[136:139], v[138:139], off
	s_nop 0
	global_load_dwordx4 v[140:143], v[140:141], off
	v_addc_co_u32_e32 v145, vcc, 0, v153, vcc
	v_add_co_u32_e32 v148, vcc, s68, v152
	s_nop 1
	v_addc_co_u32_e32 v149, vcc, 0, v153, vcc
	v_add_co_u32_e32 v154, vcc, s69, v152
	global_load_dwordx4 v[144:147], v[144:145], off offset:128
	s_nop 0
	global_load_dwordx4 v[148:151], v[148:149], off offset:128
	v_addc_co_u32_e32 v155, vcc, 0, v153, vcc
	v_add_co_u32_e32 v156, vcc, s70, v152
	s_nop 1
	v_addc_co_u32_e32 v157, vcc, 0, v153, vcc
	global_load_dwordx4 v[152:155], v[154:155], off offset:128
	s_nop 0
	global_load_dwordx4 v[156:159], v[156:157], off offset:128
	s_waitcnt lgkmcnt(8)
	v_mfma_f32_32x32x16_bf16 v[96:111], v[194:197], v[210:213], v[96:111]
	s_bitcmp1_b32 s1, 0
	s_cselect_b32 s18, 0x12000, 0
	s_add_i32 s18, s18, 0
	v_add_u32_e32 v234, s18, v188
	v_add_u32_e32 v235, s18, v193
	v_lshl_add_u64 v[180:181], v[180:181], 0, s[8:9]
	v_lshl_add_u64 v[182:183], v[182:183], 0, s[10:11]
	s_mov_b32 s0, s1
	s_cmp_eq_u32 s1, 15
	v_mfma_f32_32x32x16_bf16 v[112:127], v[194:197], v[218:221], v[112:127]
	ds_read_b64_tr_b16 v[196:197], v172 offset:11520
	s_waitcnt lgkmcnt(5)
	v_mfma_f32_32x32x16_bf16 v[64:79], v[198:201], v[210:213], v[64:79]
	v_mfma_f32_32x32x16_bf16 v[80:95], v[198:201], v[218:221], v[80:95]
	s_waitcnt lgkmcnt(4)
	v_mfma_f32_32x32x16_bf16 v[32:47], v[202:205], v[210:213], v[32:47]
	v_mfma_f32_32x32x16_bf16 v[48:63], v[202:205], v[218:221], v[48:63]
	s_waitcnt lgkmcnt(3)
	v_mfma_f32_32x32x16_bf16 v[0:15], v[206:209], v[210:213], v[0:15]
	v_mfma_f32_32x32x16_bf16 v[16:31], v[206:209], v[218:221], v[16:31]
	ds_read_b64_tr_b16 v[194:195], v172 offset:9216
	ds_read_b64_tr_b16 v[198:199], v172 offset:9280
	ds_read_b64_tr_b16 v[202:203], v172 offset:9344
	ds_read_b64_tr_b16 v[206:207], v172 offset:9408
	ds_read_b64_tr_b16 v[200:201], v172 offset:11584
	ds_read_b64_tr_b16 v[204:205], v172 offset:11648
	ds_read_b64_tr_b16 v[208:209], v172 offset:11712
	s_waitcnt lgkmcnt(6)
	v_mfma_f32_32x32x16_bf16 v[96:111], v[194:197], v[214:217], v[96:111]
	v_mfma_f32_32x32x16_bf16 v[112:127], v[194:197], v[222:225], v[112:127]
	s_waitcnt lgkmcnt(2)
	v_mfma_f32_32x32x16_bf16 v[64:79], v[198:201], v[214:217], v[64:79]
	v_mfma_f32_32x32x16_bf16 v[80:95], v[198:201], v[222:225], v[80:95]
	ds_read_b64_tr_b16 v[196:197], v172 offset:20736
	ds_read_b64_tr_b16 v[194:195], v172 offset:18432
	ds_read_b64_tr_b16 v[198:199], v172 offset:18496
	s_waitcnt lgkmcnt(4)
	v_mfma_f32_32x32x16_bf16 v[32:47], v[202:205], v[214:217], v[32:47]
	v_mfma_f32_32x32x16_bf16 v[48:63], v[202:205], v[222:225], v[48:63]
	s_waitcnt lgkmcnt(3)
	v_mfma_f32_32x32x16_bf16 v[0:15], v[206:209], v[214:217], v[0:15]
	v_mfma_f32_32x32x16_bf16 v[16:31], v[206:209], v[222:225], v[16:31]
	ds_read_b64_tr_b16 v[202:203], v172 offset:18560
	ds_read_b64_tr_b16 v[206:207], v172 offset:18624
	ds_read_b128 v[210:213], v226 offset:36928
	ds_read_b64_tr_b16 v[200:201], v172 offset:20800
	ds_read_b64_tr_b16 v[204:205], v172 offset:20864
	ds_read_b64_tr_b16 v[208:209], v172 offset:20928
	ds_read_b128 v[214:217], v226 offset:36960
	ds_read_b128 v[218:221], v226 offset:41536
	ds_read_b128 v[222:225], v226 offset:41568
	s_waitcnt lgkmcnt(6)
	v_mfma_f32_32x32x16_bf16 v[96:111], v[194:197], v[210:213], v[96:111]
	s_waitcnt lgkmcnt(1)
	v_mfma_f32_32x32x16_bf16 v[112:127], v[194:197], v[218:221], v[112:127]
	ds_read_b64_tr_b16 v[196:197], v172 offset:29952
	v_mfma_f32_32x32x16_bf16 v[64:79], v[198:201], v[210:213], v[64:79]
	v_mfma_f32_32x32x16_bf16 v[80:95], v[198:201], v[218:221], v[80:95]
	v_mfma_f32_32x32x16_bf16 v[32:47], v[202:205], v[210:213], v[32:47]
	v_mfma_f32_32x32x16_bf16 v[48:63], v[202:205], v[218:221], v[48:63]
	v_mfma_f32_32x32x16_bf16 v[0:15], v[206:209], v[210:213], v[0:15]
	v_mfma_f32_32x32x16_bf16 v[16:31], v[206:209], v[218:221], v[16:31]
	ds_read_b64_tr_b16 v[194:195], v172 offset:27648
	ds_read_b64_tr_b16 v[198:199], v172 offset:27712
	ds_read_b64_tr_b16 v[202:203], v172 offset:27776
	ds_read_b64_tr_b16 v[206:207], v172 offset:27840
	ds_read_b64_tr_b16 v[200:201], v172 offset:30016
	ds_read_b64_tr_b16 v[204:205], v172 offset:30080
	ds_read_b64_tr_b16 v[208:209], v172 offset:30144
	v_add_u32_e32 v172, s18, v170
	s_waitcnt vmcnt(7)
	ds_write_b128 v172, v[128:131]
	s_waitcnt vmcnt(6)
	ds_write_b128 v172, v[132:135] offset:9216
	s_waitcnt vmcnt(5)
	ds_write_b128 v172, v[136:139] offset:18432
	s_waitcnt vmcnt(4)
	ds_write_b128 v172, v[140:143] offset:27648
	s_waitcnt lgkmcnt(10)
	v_mfma_f32_32x32x16_bf16 v[96:111], v[194:197], v[214:217], v[96:111]
	v_mfma_f32_32x32x16_bf16 v[112:127], v[194:197], v[222:225], v[112:127]
	v_add_u32_e32 v194, s18, v176
	s_waitcnt vmcnt(3)
	ds_write_b128 v194, v[144:147] offset:36864
	s_waitcnt vmcnt(2)
	ds_write_b128 v194, v[148:151] offset:46080
	s_waitcnt vmcnt(1)
	ds_write_b128 v194, v[152:155] offset:55296
	s_waitcnt vmcnt(0)
	ds_write_b128 v194, v[156:159] offset:64512
	s_waitcnt lgkmcnt(0)
	s_barrier
	ds_read_b64_tr_b16 v[196:197], v234 offset:2304
	ds_read_b64_tr_b16 v[194:195], v234
	ds_read_b128 v[210:213], v235 offset:36864
	ds_read_b128 v[218:221], v235 offset:41472
	v_mfma_f32_32x32x16_bf16 v[64:79], v[198:201], v[214:217], v[64:79]
	v_mfma_f32_32x32x16_bf16 v[80:95], v[198:201], v[222:225], v[80:95]
	v_mfma_f32_32x32x16_bf16 v[32:47], v[202:205], v[214:217], v[32:47]
	v_mfma_f32_32x32x16_bf16 v[48:63], v[202:205], v[222:225], v[48:63]
	v_mfma_f32_32x32x16_bf16 v[0:15], v[206:209], v[214:217], v[0:15]
	v_mfma_f32_32x32x16_bf16 v[16:31], v[206:209], v[222:225], v[16:31]
	s_cbranch_scc0 .LBB0_1889
	v_add_co_u32_e32 v136, vcc, 0x780000, v160
	s_lshl_b32 s0, s16, 8
	s_nop 0
	v_addc_co_u32_e32 v137, vcc, 0, v161, vcc
	v_add_co_u32_e32 v128, vcc, 0x7a0000, v160
	s_nop 1
	v_addc_co_u32_e32 v129, vcc, 0, v161, vcc
	v_add_co_u32_e32 v132, vcc, 0x7c0000, v160
	s_nop 1
	v_addc_co_u32_e32 v133, vcc, 0, v161, vcc
	v_add_co_u32_e32 v144, vcc, 0x7e0000, v160
	global_load_dwordx4 v[128:131], v[128:129], off
	s_nop 0
	global_load_dwordx4 v[132:135], v[132:133], off
	v_addc_co_u32_e32 v145, vcc, 0, v161, vcc
	global_load_dwordx4 v[136:139], v[136:137], off
	s_nop 0
	global_load_dwordx4 v[140:143], v[162:163], off offset:1920
	s_nop 0
	global_load_dwordx4 v[144:147], v[144:145], off
	s_nop 0
	global_load_dwordx4 v[148:151], v[164:165], off offset:1920
	global_load_dwordx4 v[152:155], v[166:167], off offset:1920
	global_load_dwordx4 v[156:159], v[168:169], off offset:1920
	v_add_u32_e32 v160, v190, v192
	v_add_u32_e32 v168, 64, v160
	v_add_u32_e32 v169, 0x80, v160
	v_add_u32_e32 v170, 0xc0, v160
	v_add_u32_e32 v160, v191, v189
	v_add_u32_e32 v172, 0x9000, v160
	v_add_u32_e32 v176, 0xa200, v160
	s_add_i32 s1, 0, 0x12000
	v_add_u32_e32 v162, s1, v188
	v_add_u32_e32 v182, s1, v168
	v_add_u32_e32 v164, s1, v172
	ds_read_b64_tr_b16 v[160:161], v162
	ds_read_b64_tr_b16 v[162:163], v162 offset:2304
	ds_read_b128 v[164:167], v164
	v_add_u32_e32 v189, s1, v176
	ds_read_b64_tr_b16 v[180:181], v182
	ds_read_b64_tr_b16 v[182:183], v182 offset:2304
	ds_read_b128 v[190:193], v189
	s_waitcnt lgkmcnt(3)
	v_mfma_f32_32x32x16_bf16 v[96:111], v[160:163], v[164:167], v[96:111]
	v_add_u32_e32 v189, s1, v170
	v_add_u32_e32 v200, s71, v168
	v_add_u32_e32 v208, s71, v170
	v_add_u32_e32 v214, s72, v176
	s_mulk_i32 s21, 0x2200
	s_add_i32 s21, s1, s21
	s_or_b32 s0, s22, s0
	s_waitcnt lgkmcnt(0)
	v_mfma_f32_32x32x16_bf16 v[112:127], v[160:163], v[190:193], v[112:127]
	v_add_u32_e32 v162, s1, v169
	ds_read_b64_tr_b16 v[160:161], v162
	ds_read_b64_tr_b16 v[162:163], v162 offset:2304
	ds_read_b64_tr_b16 v[194:195], v189
	ds_read_b64_tr_b16 v[196:197], v189 offset:2304
	v_add_u32_e32 v189, s71, v188
	s_add_i32 s1, s20, s14
	v_lshlrev_b32_e32 v175, 2, v175
	v_mfma_f32_32x32x16_bf16 v[64:79], v[180:183], v[164:167], v[64:79]
	v_mfma_f32_32x32x16_bf16 v[80:95], v[180:183], v[190:193], v[80:95]
	ds_read_b64_tr_b16 v[180:181], v189
	ds_read_b64_tr_b16 v[182:183], v189 offset:2304
	ds_read_b64_tr_b16 v[198:199], v200
	ds_read_b64_tr_b16 v[200:201], v200 offset:2304
	v_add_u32_e32 v189, s71, v169
	ds_read_b64_tr_b16 v[202:203], v189
	ds_read_b64_tr_b16 v[204:205], v189 offset:2304
	ds_read_b64_tr_b16 v[206:207], v208
	ds_read_b64_tr_b16 v[208:209], v208 offset:2304
	v_add_u32_e32 v189, s72, v172
	ds_read_b128 v[210:213], v189
	ds_read_b128 v[214:217], v214
	v_add_u32_e32 v189, s73, v188
	s_waitcnt lgkmcnt(12)
	v_mfma_f32_32x32x16_bf16 v[32:47], v[160:163], v[164:167], v[32:47]
	v_mfma_f32_32x32x16_bf16 v[48:63], v[160:163], v[190:193], v[48:63]
	v_add_u32_e32 v160, s73, v168
	ds_read_b64_tr_b16 v[218:219], v189
	ds_read_b64_tr_b16 v[220:221], v189 offset:2304
	ds_read_b64_tr_b16 v[222:223], v160
	ds_read_b64_tr_b16 v[224:225], v160 offset:2304
	v_add_u32_e32 v160, s73, v169
	v_add_u32_e32 v161, s73, v170
	ds_read_b64_tr_b16 v[226:227], v160
	ds_read_b64_tr_b16 v[228:229], v160 offset:2304
	ds_read_b64_tr_b16 v[230:231], v161
	ds_read_b64_tr_b16 v[232:233], v161 offset:2304
	v_add_u32_e32 v160, s80, v172
	v_add_u32_e32 v161, s80, v176
	s_waitcnt lgkmcnt(14)
	v_mfma_f32_32x32x16_bf16 v[0:15], v[194:197], v[164:167], v[0:15]
	ds_read_b128 v[234:237], v160
	ds_read_b128 v[238:241], v161
	v_add_u32_e32 v160, s81, v188
	v_add_u32_e32 v161, s81, v168
	v_add_u32_e32 v162, s81, v170
	v_add_u32_e32 v164, s82, v172
	v_add_u32_e32 v165, s82, v176
	v_lshlrev_b32_e32 v172, 1, v178
	v_mfma_f32_32x32x16_bf16 v[16:31], v[194:197], v[190:193], v[16:31]
	v_lshrrev_b32_e32 v194, 3, v187
	ds_read_b64_tr_b16 v[188:189], v160
	ds_read_b64_tr_b16 v[190:191], v160 offset:2304
	ds_read_b64_tr_b16 v[242:243], v161
	ds_read_b64_tr_b16 v[244:245], v161 offset:2304
	v_add_u32_e32 v160, s81, v169
	ds_read_b64_tr_b16 v[246:247], v160
	ds_read_b64_tr_b16 v[248:249], v160 offset:2304
	ds_read_b64_tr_b16 v[160:161], v162
	ds_read_b64_tr_b16 v[162:163], v162 offset:2304
	ds_read_b128 v[250:253], v164
	ds_read_b128 v[164:167], v165
	s_waitcnt vmcnt(5)
	ds_write_b128 v177, v[136:139]
	ds_write_b128 v177, v[128:131] offset:9216
	ds_write_b128 v177, v[132:135] offset:18432
	s_waitcnt vmcnt(3)
	ds_write_b128 v177, v[144:147] offset:27648
	ds_write_b128 v171, v[140:143] offset:36864
	s_waitcnt vmcnt(2)
	ds_write_b128 v171, v[148:151] offset:46080
	s_waitcnt vmcnt(1)
	ds_write_b128 v171, v[152:155] offset:55296
	s_waitcnt vmcnt(0)
	ds_write_b128 v171, v[156:159] offset:64512
	s_waitcnt lgkmcnt(14)
	v_mfma_f32_32x32x16_bf16 v[96:111], v[180:183], v[210:213], v[96:111]
	s_waitcnt lgkmcnt(0)
	s_barrier
	v_or_b32_e32 v176, s0, v178
	v_ashrrev_i32_e32 v177, 31, v176
	v_lshl_add_u32 v195, v178, 2, s21
	v_mul_u32_u24_e32 v178, 0x440, v186
	v_mfma_f32_32x32x16_bf16 v[112:127], v[180:183], v[214:217], v[112:127]
	v_or_b32_e32 v180, s1, v194
	v_ashrrev_i32_e32 v181, 31, v180
	v_or_b32_e32 v130, 8, v180
	s_ashr_i32 s1, s0, 31
	v_lshlrev_b64 v[128:129], 11, v[180:181]
	v_ashrrev_i32_e32 v131, 31, v130
	v_lshl_add_u64 v[128:129], s[6:7], 0, v[128:129]
	s_lshl_b64 s[18:19], s[0:1], 1
	v_lshlrev_b64 v[130:131], 11, v[130:131]
	v_lshl_add_u64 v[128:129], v[128:129], 0, s[18:19]
	v_lshl_add_u64 v[130:131], s[6:7], 0, v[130:131]
	v_lshl_add_u64 v[128:129], v[128:129], 0, v[172:173]
	v_lshl_add_u64 v[130:131], v[130:131], 0, s[18:19]
	v_mfma_f32_32x32x16_bf16 v[64:79], v[198:201], v[210:213], v[64:79]
	v_lshl_add_u64 v[130:131], v[130:131], 0, v[172:173]
	s_ashr_i32 s0, s14, 12
	s_mulk_i32 s0, 0xc00
	s_ashr_i32 s1, s0, 31
	s_lshl_b64 s[0:1], s[0:1], 2
	s_add_u32 s0, s78, s0
	s_addc_u32 s1, s79, s1
	v_mfma_f32_32x32x16_bf16 v[80:95], v[198:201], v[214:217], v[80:95]
	global_load_dwordx4 v[196:199], v[128:129], off
	global_load_dwordx4 v[168:171], v[130:131], off
	v_or_b32_e32 v128, 16, v180
	v_ashrrev_i32_e32 v129, 31, v128
	v_or_b32_e32 v130, 24, v180
	v_lshlrev_b64 v[128:129], 11, v[128:129]
	v_ashrrev_i32_e32 v131, 31, v130
	v_lshl_add_u64 v[128:129], s[6:7], 0, v[128:129]
	v_lshlrev_b64 v[130:131], 11, v[130:131]
	v_lshl_add_u64 v[128:129], v[128:129], 0, s[18:19]
	v_lshl_add_u64 v[130:131], s[6:7], 0, v[130:131]
	v_lshl_add_u64 v[128:129], v[128:129], 0, v[172:173]
	v_lshl_add_u64 v[130:131], v[130:131], 0, s[18:19]
	v_lshl_add_u64 v[130:131], v[130:131], 0, v[172:173]
	global_load_dwordx4 v[156:159], v[128:129], off
	global_load_dwordx4 v[152:155], v[130:131], off
	v_lshl_add_u64 v[128:129], v[176:177], 2, s[0:1]
	v_lshl_add_u64 v[130:131], v[128:129], 0, s[12:13]
	v_add_co_u32_e32 v128, vcc, s83, v128
	v_or_b32_e32 v136, 32, v180
	s_nop 0
	v_addc_co_u32_e32 v129, vcc, 0, v129, vcc
	global_load_dwordx4 v[132:135], v[128:129], off
	s_nop 0
	global_load_dwordx4 v[128:131], v[130:131], off offset:16
	v_or_b32_e32 v138, 40, v180
	v_ashrrev_i32_e32 v137, 31, v136
	v_ashrrev_i32_e32 v139, 31, v138
	v_lshlrev_b64 v[136:137], 11, v[136:137]
	v_lshlrev_b64 v[138:139], 11, v[138:139]
	v_lshl_add_u64 v[136:137], s[6:7], 0, v[136:137]
	v_lshl_add_u64 v[138:139], s[6:7], 0, v[138:139]
	v_lshl_add_u64 v[136:137], v[136:137], 0, s[18:19]
	v_lshl_add_u64 v[138:139], v[138:139], 0, s[18:19]
	v_lshl_add_u64 v[136:137], v[136:137], 0, v[172:173]
	v_lshl_add_u64 v[138:139], v[138:139], 0, v[172:173]
	global_load_dwordx4 v[148:151], v[136:137], off
	global_load_dwordx4 v[144:147], v[138:139], off
	v_or_b32_e32 v136, 48, v180
	v_or_b32_e32 v138, 56, v180
	v_ashrrev_i32_e32 v137, 31, v136
	v_ashrrev_i32_e32 v139, 31, v138
	v_lshlrev_b64 v[136:137], 11, v[136:137]
	v_lshlrev_b64 v[138:139], 11, v[138:139]
	v_lshl_add_u64 v[136:137], s[6:7], 0, v[136:137]
	v_lshl_add_u64 v[138:139], s[6:7], 0, v[138:139]
	v_lshl_add_u64 v[136:137], v[136:137], 0, s[18:19]
	v_lshl_add_u64 v[138:139], v[138:139], 0, s[18:19]
	v_lshl_add_u64 v[136:137], v[136:137], 0, v[172:173]
	v_lshl_add_u64 v[138:139], v[138:139], 0, v[172:173]
	global_load_dwordx4 v[140:143], v[136:137], off
	s_nop 0
	global_load_dwordx4 v[136:139], v[138:139], off
	v_mfma_f32_32x32x16_bf16 v[96:111], v[218:221], v[234:237], v[96:111]
	v_add3_u32 v186, s21, v175, v178
	v_add_u32_e32 v187, 0x800, v186
	v_add_u32_e32 v192, 0x1a00, v186
	v_add_u32_e32 v193, 0x1c00, v186
	v_or_b32_e32 v181, s20, v194
	v_cmp_eq_u32_e32 vcc, 0, v185
	v_mfma_f32_32x32x16_bf16 v[112:127], v[218:221], v[238:241], v[112:127]
	v_mfma_f32_32x32x16_bf16 v[96:111], v[188:191], v[250:253], v[96:111]
	v_mfma_f32_32x32x16_bf16 v[112:127], v[188:191], v[164:167], v[112:127]
	s_nop 11
	ds_write2_b32 v186, v96, v112 offset1:32
	ds_write2_b32 v186, v97, v113 offset0:68 offset1:100
	ds_write2_b32 v186, v98, v114 offset0:136 offset1:168
	ds_write2_b32 v186, v99, v115 offset0:204 offset1:236
	v_add_u32_e32 v189, 0xa00, v186
	v_add_u32_e32 v188, 0x1000, v186
	v_and_b32_e32 v97, 64, v184
	ds_write2_b32 v187, v100, v116 offset0:32 offset1:64
	ds_write2_b32 v187, v101, v117 offset0:100 offset1:132
	ds_write2_b32 v187, v102, v118 offset0:168 offset1:200
	ds_write2_b32 v189, v103, v119 offset0:108 offset1:140
	ds_write2_b32 v188, v104, v120 offset0:64 offset1:96
	ds_write2_b32 v188, v105, v121 offset0:132 offset1:164
	ds_write2_b32 v188, v106, v122 offset0:200 offset1:232
	v_add_u32_e32 v190, 0x1400, v186
	v_add_u32_e32 v191, 0x1800, v186
	v_xor_b32_e32 v96, 1, v184
	v_add_u32_e32 v106, 64, v97
	ds_write2_b32 v190, v107, v123 offset0:12 offset1:44
	ds_write2_b32 v191, v108, v124 offset0:96 offset1:128
	ds_write2_b32 v191, v109, v125 offset0:164 offset1:196
	ds_write2_b32 v192, v110, v126 offset0:104 offset1:136
	ds_write2_b32 v193, v111, v127 offset0:44 offset1:76
	v_cmp_lt_i32_e64 s[0:1], v96, v106
	s_waitcnt lgkmcnt(0)
	v_mad_u32_u24 v100, v194, s84, v195
	s_waitcnt vmcnt(9)
	v_lshlrev_b32_e32 v104, 16, v196
	v_cndmask_b32_e64 v96, v184, v96, s[0:1]
	v_lshlrev_b32_e32 v175, 2, v96
	ds_read_b128 v[96:99], v100
	ds_read_b128 v[100:103], v100 offset:16
	v_and_b32_e32 v105, 0xffff0000, v196
	v_mfma_f32_32x32x16_bf16 v[32:47], v[202:205], v[210:213], v[32:47]
	v_xor_b32_e32 v107, 2, v184
	s_waitcnt vmcnt(5) lgkmcnt(1)
	v_fma_f32 v112, v132, v96, v104
	v_fma_f32 v113, v133, v97, v105
	v_lshlrev_b32_e32 v96, 16, v197
	v_and_b32_e32 v97, 0xffff0000, v197
	v_pk_fma_f32 v[114:115], v[134:135], v[98:99], v[96:97]
	v_lshlrev_b32_e32 v96, 16, v198
	v_and_b32_e32 v97, 0xffff0000, v198
	v_mfma_f32_32x32x16_bf16 v[48:63], v[202:205], v[214:217], v[48:63]
	s_waitcnt vmcnt(4) lgkmcnt(0)
	v_fma_f32 v116, v128, v100, v96
	v_fma_f32 v117, v129, v101, v97
	v_lshlrev_b32_e32 v96, 16, v199
	v_and_b32_e32 v97, 0xffff0000, v199
	v_pk_fma_f32 v[118:119], v[130:131], v[102:103], v[96:97]
	v_pk_mul_f32 v[96:97], v[112:113], v[112:113]
	v_pk_mul_f32 v[100:101], v[116:117], v[116:117]
	v_pk_mul_f32 v[98:99], v[114:115], v[114:115]
	v_mfma_f32_32x32x16_bf16 v[0:15], v[206:209], v[210:213], v[0:15]
	v_mul_f32_e64 v102, v118, v118
	v_mul_f32_e64 v103, v119, v119
	v_add_f32_e32 v96, v96, v97
	v_add_f32_e32 v97, v100, v101
	v_add_f32_e32 v96, v98, v96
	v_add_f32_e32 v97, v102, v97
	v_add_f32_e32 v96, v99, v96
	v_add_f32_e32 v97, v103, v97
	v_mfma_f32_32x32x16_bf16 v[16:31], v[206:209], v[214:217], v[16:31]
	v_add_f32_e32 v96, v96, v97
	ds_bpermute_b32 v97, v175, v96
	v_cmp_lt_i32_e64 s[0:1], v107, v106
	s_waitcnt lgkmcnt(0)
	v_add_f32_e32 v96, v96, v97
	v_mfma_f32_32x32x16_bf16 v[64:79], v[222:225], v[234:237], v[64:79]
	v_cndmask_b32_e64 v98, v184, v107, s[0:1]
	v_lshlrev_b32_e32 v178, 2, v98
	ds_bpermute_b32 v97, v178, v96
	v_xor_b32_e32 v98, 4, v184
	v_cmp_lt_i32_e64 s[0:1], v98, v106
	s_waitcnt lgkmcnt(0)
	v_add_f32_e32 v96, v96, v97
	v_mfma_f32_32x32x16_bf16 v[80:95], v[222:225], v[238:241], v[80:95]
	v_cndmask_b32_e64 v98, v184, v98, s[0:1]
	v_lshlrev_b32_e32 v183, 2, v98
	ds_bpermute_b32 v97, v183, v96
	s_lshl_b32 s0, s15, 2
	s_add_i32 s15, s0, 0
	s_add_i32 s15, s15, 0x24000
	v_lshl_add_u32 v182, v181, 4, s15
	v_mfma_f32_32x32x16_bf16 v[32:47], v[226:229], v[234:237], v[32:47]
	v_mfma_f32_32x32x16_bf16 v[48:63], v[226:229], v[238:241], v[48:63]
	v_mfma_f32_32x32x16_bf16 v[0:15], v[230:233], v[234:237], v[0:15]
	v_mfma_f32_32x32x16_bf16 v[16:31], v[230:233], v[238:241], v[16:31]
	v_mfma_f32_32x32x16_bf16 v[64:79], v[242:245], v[250:253], v[64:79]
	v_mfma_f32_32x32x16_bf16 v[80:95], v[242:245], v[164:167], v[80:95]
	v_mfma_f32_32x32x16_bf16 v[32:47], v[246:249], v[250:253], v[32:47]
	v_mfma_f32_32x32x16_bf16 v[48:63], v[246:249], v[164:167], v[48:63]
	v_mfma_f32_32x32x16_bf16 v[0:15], v[160:163], v[250:253], v[0:15]
	v_mfma_f32_32x32x16_bf16 v[16:31], v[160:163], v[164:167], v[16:31]
	s_and_saveexec_b64 s[0:1], vcc
	s_cbranch_execz .LBB0_1892
	s_waitcnt lgkmcnt(0)
	v_add_f32_e32 v96, v96, v97
	ds_write_b32 v182, v96
